# MRG moved to d_out scratch; grid barrier after round-0 w_o GEMM skipped (no ordering needed any more)
# baseline (speedup 1.0000x reference)
; #define LAS __attribute__((address_space(3)))
; __global__ void __launch_bounds__(NTHR, 2) fwd_kernel(Args args) {
;     ...
;     Ptrs A; A.x = args.in[0]; A.mix_norm = args.in[1]; A.w_in = args.in[2]; A.w_a = args.in[3]; A.w_b = args.in[4]; A.w_o = args.in[5]; A.ffn_norm = args.in[6]; A.w_up = args.in[7]; A.w_down = args.in[8]; A.final_norm = args.in[9];
;     A.out = args.out; A.ws = args.ws;
;     unsigned char* ws = args.ws;
;     unsigned* ctl = (unsigned*)(ws + WS_CTL);
;     bf16* XN = (bf16*)(ws + WS_XN); bf16* Pb = (bf16*)(ws + WS_P); bf16* Gb = (bf16*)(ws + WS_G); bf16* COMB = (bf16*)(ws + WS_COMB); bf16* RET = (bf16*)(ws + WS_RET);
;     bf16* SCR = (bf16*)(ws + WS_SCR); bf16* MRG = (bf16*)(ws + WS_MRG); bf16* Hb = (bf16*)(ws + WS_H);
;     float* PART = (float*)(ws + WS_PART); float* LSE = (float*)(ws + WS_LSE);
;     const float* ropeA = (const float*)(ws + WS_ROPEA); const float* ropeR = (const float*)(ws + WS_ROPER);
;     if (F.tid < 8) ((LAS unsigned*)(F.lds + LDS_BYTES - 32))[F.tid] = 0u;
;     __syncthreads();
;     XcdBarrier bar = xcd_barrier_post((unsigned*)(ws + WS_BAR), (volatile LAS unsigned*)(F.lds + LDS_BYTES - 32));
;     const int lo = args.ph_lo, hi = args.ph_hi; int ph = 0;
.LBB0_126:
.LBB0_127:
	s_add_u32 s0, s62, 0x5800000
	s_addc_u32 s1, s63, 0
	s_add_u32 s74, s62, 0x9800000
	s_addc_u32 s75, s63, 0
	s_add_u32 s66, s62, 0x18800000
	v_writelane_b32 v253, s0, 9
	s_addc_u32 s67, s63, 0
	s_mul_i32 s4, s79, s78
	v_writelane_b32 v253, s1, 10
	s_add_u32 s0, s62, 0x1c800000
	s_addc_u32 s93, s63, 0
	s_add_u32 s2, s62, 0x1d800000
	v_writelane_b32 v253, s0, 11
	s_addc_u32 s0, s63, 0
	v_writelane_b32 v253, s0, 12
	s_add_u32 s0, s60, 0x4000000
	s_addc_u32 s1, s61, 0
	v_writelane_b32 v253, s0, 13
	s_mov_b32 s71, 0
	v_lshrrev_b32_e32 v1, 20, v0
	v_writelane_b32 v253, s1, 14
	s_add_u32 s0, s62, 0x300000
	s_addc_u32 s1, s63, 0
	v_writelane_b32 v253, s0, 15
	v_lshrrev_b32_e32 v0, 10, v0
	v_or_b32_e32 v0, v0, v1
	v_writelane_b32 v253, s1, 16
	s_add_u32 s0, s62, 0x500000
	s_addc_u32 s1, s63, 0
	v_writelane_b32 v253, s0, 17
	v_mbcnt_lo_u32_b32 v2, -1, 0
	v_mov_b32_e32 v225, 0x358637bd
	v_writelane_b32 v253, s1, 18
	s_add_u32 s0, s62, 0x10000
	s_addc_u32 s1, s63, 0
	s_add_u32 s86, s62, 0x100000
	v_writelane_b32 v253, s0, 19
	s_addc_u32 s87, s63, 0
	v_mov_b32_e32 v226, 0x260
	v_writelane_b32 v253, s1, 20
	s_add_u32 s0, s62, 0x800000
	v_writelane_b32 v253, s0, 21
	s_addc_u32 s0, s63, 0
	s_ashr_i32 s79, s78, 31
	s_add_u32 s88, s62, 0x14800000
	s_addc_u32 s89, s63, 0
	s_add_u32 s90, s62, 0x12800000
	s_addc_u32 s91, s63, 0
	s_cmp_gt_i32 s76, -1
	v_writelane_b32 v253, s0, 22
	s_cselect_b64 s[0:1], -1, 0
	v_writelane_b32 v253, s0, 23
	v_mov_b32_e32 v1, 0
	v_mov_b32_e32 v227, 1
	v_writelane_b32 v253, s1, 24
	s_add_u32 s0, s62, 0x1200
	s_addc_u32 s1, s63, 0
	v_writelane_b32 v253, s0, 25
	v_mov_b64_e32 v[162:163], 0x980
	v_mov_b64_e32 v[164:165], 0x97f
	v_writelane_b32 v253, s1, 26
	s_add_u32 s0, s62, 0x1400
	s_addc_u32 s1, s63, 0
	v_writelane_b32 v253, s0, 27
	v_mov_b32_e32 v228, 0xfcf
	v_mov_b32_e32 v229, 0xbbb906ce
	v_writelane_b32 v253, s1, 28
	s_add_u32 s0, s62, 0x1500
	s_addc_u32 s1, s63, 0
	v_writelane_b32 v253, s0, 29
	v_mov_b32_e32 v230, 0xbc3963dd
	v_mov_b32_e32 v231, 0xffffff10
	v_writelane_b32 v253, s1, 30
	s_add_u32 s0, s62, 0x1600
	s_addc_u32 s1, s63, 0
	v_writelane_b32 v253, s0, 31
	v_mov_b32_e32 v232, 0xff61b1e6
	v_mbcnt_hi_u32_b32 v233, -1, v2
	v_writelane_b32 v253, s1, 32
	s_add_u32 s0, s62, 0x1700
	s_addc_u32 s1, s63, 0
	v_writelane_b32 v253, s0, 33
	v_mov_b32_e32 v234, 0x1c800000
	v_mov_b64_e32 v[166:167], 0x100
	v_writelane_b32 v253, s1, 34
	s_add_u32 s0, s62, 0x1800
	s_addc_u32 s1, s63, 0
	v_writelane_b32 v253, s0, 35
	v_mov_b64_e32 v[168:169], 0xff
	v_mov_b64_e32 v[170:171], 0x7ff
	v_writelane_b32 v253, s1, 36
	s_add_u32 s0, s62, 0x1900
	s_addc_u32 s1, s63, 0
	v_writelane_b32 v253, s0, 37
	v_mov_b64_e32 v[176:177], 0x1ff
	s_mov_b32 s85, 0x11000
	v_writelane_b32 v253, s1, 38
	s_add_u32 s0, s62, 0x1a00
	s_addc_u32 s1, s63, 0
	v_writelane_b32 v253, s0, 39
	s_movk_i32 s81, 0x1000
	s_movk_i32 s80, 0x4000
	v_writelane_b32 v253, s1, 40
	s_add_u32 s0, s62, 0x1b00
	s_addc_u32 s1, s63, 0
	v_writelane_b32 v253, s0, 41
	s_mov_b32 s30, 0x8000
	s_movk_i32 s69, 0x110
	v_writelane_b32 v253, s1, 42
	s_add_u32 s0, s62, 0x1c00
	s_addc_u32 s1, s63, 0
	v_writelane_b32 v253, s0, 43
	s_movk_i32 s83, 0x210
	s_mov_b32 s56, 0x21000
	v_writelane_b32 v253, s1, 44
	s_add_u32 s0, s62, 0x1d00
	s_addc_u32 s1, s63, 0
	v_writelane_b32 v253, s0, 45
	s_mov_b64 s[10:11], 0x80
	s_mov_b32 s12, 0x3db504f3
	v_writelane_b32 v253, s1, 46
	s_add_u32 s0, s62, 0x1e00
	s_addc_u32 s1, s63, 0
	v_writelane_b32 v253, s0, 47
	s_nop 1
	v_writelane_b32 v253, s1, 48
	s_add_u32 s0, s62, 0x1f00
	s_addc_u32 s1, s63, 0
	v_writelane_b32 v253, s0, 49
	s_nop 1
	v_writelane_b32 v253, s1, 50
	s_add_u32 s0, s62, 0x2000
	s_addc_u32 s1, s63, 0
	v_writelane_b32 v253, s0, 51
	s_nop 1
	v_writelane_b32 v253, s1, 52
	s_add_u32 s0, s62, 0x2100
	s_addc_u32 s1, s63, 0
	v_writelane_b32 v253, s0, 53
	s_nop 1
	v_writelane_b32 v253, s1, 54
	s_add_u32 s0, s62, 0x2200
	s_addc_u32 s1, s63, 0
	v_writelane_b32 v253, s0, 55
	s_nop 1
	v_writelane_b32 v253, s1, 56
	s_add_u32 s0, s62, 0x2300
	s_addc_u32 s1, s63, 0
	v_writelane_b32 v253, s0, 57
	s_cmp_eq_u32 s37, 15
	s_nop 0
	v_writelane_b32 v253, s1, 58
	s_cselect_b64 s[0:1], -1, 0
	v_writelane_b32 v253, s0, 59
	s_cmp_eq_u32 s37, 14
	s_nop 0
	v_writelane_b32 v253, s1, 60
	s_cselect_b64 s[0:1], -1, 0
	v_writelane_b32 v253, s0, 61
	s_cmp_eq_u32 s37, 13
	s_nop 0
	v_writelane_b32 v253, s1, 62
	s_cselect_b64 s[0:1], -1, 0
	v_writelane_b32 v253, s0, 63
	s_cmp_eq_u32 s37, 12
	s_nop 0
	v_writelane_b32 v254, s1, 0
	s_cselect_b64 s[0:1], -1, 0
	v_writelane_b32 v254, s0, 1
	s_cmp_eq_u32 s37, 11
	s_nop 0
	v_writelane_b32 v254, s1, 2
	s_cselect_b64 s[0:1], -1, 0
	v_writelane_b32 v254, s0, 3
	s_cmp_eq_u32 s37, 10
	s_nop 0
	v_writelane_b32 v254, s1, 4
	s_cselect_b64 s[0:1], -1, 0
	v_writelane_b32 v254, s0, 5
	s_cmp_eq_u32 s37, 9
	s_nop 0
	v_writelane_b32 v254, s1, 6
	s_cselect_b64 s[0:1], -1, 0
	v_writelane_b32 v254, s0, 7
	s_cmp_eq_u32 s37, 8
	s_nop 0
	v_writelane_b32 v254, s1, 8
	s_cselect_b64 s[0:1], -1, 0
	v_writelane_b32 v254, s0, 9
	s_cmp_eq_u32 s37, 7
	s_nop 0
	v_writelane_b32 v254, s1, 10
	s_cselect_b64 s[0:1], -1, 0
	v_writelane_b32 v254, s0, 11
	s_cmp_eq_u32 s37, 6
	s_nop 0
	v_writelane_b32 v254, s1, 12
	s_cselect_b64 s[0:1], -1, 0
	v_writelane_b32 v254, s0, 13
	s_cmp_eq_u32 s37, 5
	s_nop 0
	v_writelane_b32 v254, s1, 14
	s_cselect_b64 s[0:1], -1, 0
	v_writelane_b32 v254, s0, 15
	s_cmp_eq_u32 s37, 4
	s_nop 0
	v_writelane_b32 v254, s1, 16
	s_cselect_b64 s[0:1], -1, 0
	v_writelane_b32 v254, s0, 17
	s_cmp_eq_u32 s37, 3
	s_nop 0
	v_writelane_b32 v254, s1, 18
	s_cselect_b64 s[0:1], -1, 0
	v_writelane_b32 v254, s0, 19
	s_cmp_eq_u32 s37, 2
	s_nop 0
; #define LAS __attribute__((address_space(3)))
; __device__ __forceinline__ void attn_compute(LAS unsigned char* lds, int lane, int w, int u, bf16* P, float* LSE, bool do_store) {
;     ...
;     for (int ks = 0; ks < 2; ++ks) qf[ks] = *(LAS bf16x8*)(lds + AT_Q + (16 * w + fr) * AT_P + (32 * ks + 8 * fq) * 2);
;     f32x4 sc[10];
; #pragma unroll
;     for (int tt = 0; tt < 10; ++tt) { const int t = (w + tt) < 15 ? (w + tt) : 15; f32x4 a = (f32x4){0.f, 0.f, 0.f, 0.f};
; #pragma unroll
;         for (int ks = 0; ks < 2; ++ks) { const bf16x8 kf = *(LAS bf16x8*)(lds + AT_K + (16 * t + fr) * AT_P + (32 * ks + 8 * fq) * 2); a = MFMA16(kf, qf[ks], a); }
;         sc[tt] = a; if (tt & 1) __builtin_amdgcn_sched_barrier(0); }
;     float mx = -3.0e38f;
; #pragma unroll
;     for (int tt = 0; tt < 10; ++tt)
; #pragma unroll
;         for (int i = 0; i < 4; ++i) { const int kr = 16 * tt + 4 * fq + i; const bool valid = (kr >= fr) && (kr <= fr + 128) && (n > 0 || (16 * w + kr >= 128));
;             const float s = valid ? sc[tt][i] : -3.0e38f; sc[tt][i] = s; mx = fmaxf(mx, s); }
;     mx = fmaxf(mx, __shfl_xor(mx, 16)); mx = fmaxf(mx, __shfl_xor(mx, 32));
;     const float cexp = 0.125f * 1.4426950408889634f; float den = 0.f;
; #pragma unroll
;     for (int tt = 0; tt < 10; ++tt)
; #pragma unroll
;         for (int i = 0; i < 4; ++i) { const float p = __builtin_amdgcn_exp2f((sc[tt][i] - mx) * cexp); sc[tt][i] = p; den += p; }
;     den += __shfl_xor(den, 16); den += __shfl_xor(den, 32);
;     f32x4 o[4];
; #pragma unroll
;     for (int dt = 0; dt < 4; ++dt) o[dt] = (f32x4){0.f, 0.f, 0.f, 0.f};
;     const int tq = fr >> 2, tp = fr & 3;
; #pragma unroll
;     for (int s = 0; s < 5; ++s) { const int t0 = (w + 2 * s) < 15 ? (w + 2 * s) : 15, t1 = (w + 2 * s + 1) < 15 ? (w + 2 * s + 1) : 15;
;         u32x4 pw; pw.x = cvtpk(sc[2 * s][0], sc[2 * s][1]); pw.y = cvtpk(sc[2 * s][2], sc[2 * s][3]); pw.z = cvtpk(sc[2 * s + 1][0], sc[2 * s + 1][1]); pw.w = cvtpk(sc[2 * s + 1][2], sc[2 * s + 1][3]);
;         const bf16x8 pf = __builtin_bit_cast(bf16x8, pw);
; #pragma unroll
;         for (int dt = 0; dt < 4; ++dt) { const s16x4 lo = trr(lds + AT_V + (16 * t0 + 4 * fq + tq) * AT_P + (16 * dt + 4 * tp) * 2), hi = trr(lds + AT_V + (16 * t1 + 4 * fq + tq) * AT_P + (16 * dt + 4 * tp) * 2);
;             o[dt] = MFMA16(cat8(lo, hi), pf, o[dt]); } __builtin_amdgcn_sched_barrier(0); }
	v_writelane_b32 v254, s1, 20
	s_cselect_b64 s[0:1], -1, 0
	v_writelane_b32 v254, s0, 21
	s_cmp_eq_u32 s37, 1
	s_nop 0
	v_writelane_b32 v254, s1, 22
	s_cselect_b64 s[0:1], -1, 0
	v_writelane_b32 v254, s0, 23
	s_cmp_eq_u32 s37, 0
	s_nop 0
	v_writelane_b32 v254, s1, 24
	s_cselect_b64 s[0:1], -1, 0
	v_writelane_b32 v254, s0, 25
	s_nop 1
	v_writelane_b32 v254, s1, 26
	s_lshl_b32 s0, s37, 8
	s_add_u32 s0, s50, s0
	s_addc_u32 s1, s51, 0
	s_add_u32 s6, s0, 0x1400
	s_addc_u32 s7, s1, 0
	v_writelane_b32 v254, s6, 27
	s_add_u32 s0, s0, 0x2400
	s_addc_u32 s1, s1, 0
	v_writelane_b32 v254, s7, 28
	v_writelane_b32 v254, s0, 29
	s_mov_b32 s6, s64
	s_mov_b32 s7, s71
	v_writelane_b32 v254, s1, 30
	s_add_u32 s0, s62, 0x4400
	s_addc_u32 s1, s63, 0
	v_writelane_b32 v254, s0, 31
	s_mov_b32 s37, 0x10000
	s_nop 0
	v_writelane_b32 v254, s1, 32
	s_add_u32 s0, s62, 0x4500
	s_addc_u32 s1, s63, 0
	v_writelane_b32 v254, s0, 33
	s_add_u32 s48, s62, 0x13800000
	s_addc_u32 s49, s63, 0
	v_writelane_b32 v254, s1, 34
	s_and_b32 s0, s33, 0xffffffc0
	s_add_i32 s92, s0, 0
	s_add_i32 s92, s92, 0x11000
	s_lshl_b64 s[0:1], s[6:7], 13
	s_add_u32 s0, s60, s0
	s_addc_u32 s1, s61, s1
	v_writelane_b32 v254, s0, 35
	s_nop 1
	v_writelane_b32 v254, s1, 36
	s_mul_i32 s0, s4, s36
	v_writelane_b32 v254, s0, 37
	s_movk_i32 s0, 0x3ff
	v_and_or_b32 v0, v0, s0, v224
	s_add_u32 s0, s62, 0x30000
	s_addc_u32 s1, s63, 0
	v_writelane_b32 v254, s0, 38
	s_add_i32 s5, s64, 6
	s_mov_b32 s36, 0x20000
	v_writelane_b32 v254, s1, 39
	s_min_i32 s0, s64, 15
	s_lshl_b32 s0, s0, 4
	v_writelane_b32 v254, s0, 40
	s_min_i32 s0, s64, 14
	s_lshl_b32 s0, s0, 4
	s_add_i32 s0, s0, 16
	v_writelane_b32 v254, s0, 41
	s_add_i32 s0, s64, 2
	s_min_i32 s1, s0, 15
	s_lshl_b32 s1, s1, 4
	v_writelane_b32 v254, s1, 42
	s_min_i32 s1, s64, 12
	s_lshl_b32 s1, s1, 4
	s_add_i32 s1, s1, 48
	v_writelane_b32 v254, s1, 43
	s_add_i32 s1, s64, 4
	s_min_i32 s3, s1, 15
	s_lshl_b32 s3, s3, 4
	v_writelane_b32 v254, s3, 44
	s_min_i32 s3, s64, 10
	s_lshl_b32 s3, s3, 4
	s_addk_i32 s3, 0x50
	v_writelane_b32 v254, s3, 45
	s_min_i32 s3, s5, 15
	s_lshl_b32 s3, s3, 4
	v_writelane_b32 v254, s3, 46
	s_min_i32 s3, s64, 8
	s_lshl_b32 s3, s3, 4
	s_addk_i32 s3, 0x70
	v_writelane_b32 v254, s3, 47
	s_add_i32 s3, s64, 8
	s_min_i32 s4, s3, 15
	s_lshl_b32 s4, s4, 4
	v_writelane_b32 v254, s4, 48
	s_lshl_b32 s4, s64, 4
	s_cmpk_gt_u32 s33, 0x1ff
	s_cselect_b64 s[8:9], -1, 0
	v_writelane_b32 v254, s8, 49
	s_cmpk_gt_u32 s33, 0x1bf
	s_nop 0
	v_writelane_b32 v254, s9, 50
	s_cselect_b64 s[8:9], -1, 0
	v_writelane_b32 v254, s8, 51
	s_cmpk_gt_u32 s33, 0x17f
	s_nop 0
	v_writelane_b32 v254, s9, 52
	s_cselect_b64 s[8:9], -1, 0
	v_writelane_b32 v254, s8, 53
	s_cmpk_gt_u32 s33, 0x13f
	s_nop 0
	v_writelane_b32 v254, s9, 54
	s_cselect_b64 s[8:9], -1, 0
	v_writelane_b32 v254, s8, 55
	s_cmpk_gt_u32 s33, 0xff
	s_nop 0
	v_writelane_b32 v254, s9, 56
	s_cselect_b64 s[8:9], -1, 0
	v_writelane_b32 v254, s8, 57
	s_cmpk_gt_u32 s33, 0xbf
	s_nop 0
	v_writelane_b32 v254, s9, 58
	s_cselect_b64 s[8:9], -1, 0
	v_writelane_b32 v254, s8, 59
	s_cmpk_gt_u32 s33, 0x7f
	s_nop 0
	v_writelane_b32 v254, s9, 60
	s_cselect_b64 s[8:9], -1, 0
	v_writelane_b32 v254, s8, 61
	s_cmp_gt_u32 s33, 63
	s_nop 0
	v_writelane_b32 v254, s9, 62
	s_cselect_b64 s[8:9], -1, 0
	s_cmpk_lt_u32 s33, 0x3c0
	v_writelane_b32 v254, s8, 63
	s_cselect_b32 s7, s4, 0xf0
	s_nop 0
	v_writelane_b32 v255, s9, 0
	v_writelane_b32 v255, s7, 1
	v_writelane_b32 v255, s4, 2
	s_add_i32 s4, s4, 16
	s_cmpk_lt_u32 s33, 0x380
	s_cselect_b32 s4, s4, 0xf0
	s_lshl_b32 s0, s0, 4
	s_cmpk_lt_u32 s33, 0x340
	v_writelane_b32 v255, s4, 3
	s_cselect_b32 s4, s0, 0xf0
	s_add_i32 s0, s0, 16
	s_cmpk_lt_u32 s33, 0x300
	v_writelane_b32 v255, s4, 4
	s_cselect_b32 s0, s0, 0xf0
	v_writelane_b32 v255, s0, 5
	s_lshl_b32 s0, s1, 4
	s_cmpk_lt_u32 s33, 0x2c0
	s_cselect_b32 s1, s0, 0xf0
	s_add_i32 s0, s0, 16
	s_cmpk_lt_u32 s33, 0x280
	v_writelane_b32 v255, s1, 6
	s_cselect_b32 s0, s0, 0xf0
	v_writelane_b32 v255, s0, 7
	s_lshl_b32 s0, s5, 4
	s_cmpk_lt_u32 s33, 0x240
	s_cselect_b32 s1, s0, 0xf0
	s_add_i32 s0, s0, 16
	s_cmpk_lt_u32 s33, 0x200
	v_writelane_b32 v255, s1, 8
	s_cselect_b32 s0, s0, 0xf0
	v_writelane_b32 v255, s0, 9
	s_lshl_b32 s0, s3, 4
	s_cmpk_lt_u32 s33, 0x1c0
	s_cselect_b32 s1, s0, 0xf0
	s_add_i32 s0, s0, 16
	s_cmpk_lt_u32 s33, 0x180
	v_writelane_b32 v255, s1, 10
	s_cselect_b32 s0, s0, 0xf0
	s_cmpk_lg_i32 s78, 0x100
	v_writelane_b32 v255, s0, 11
	s_cselect_b64 s[0:1], -1, 0
	v_writelane_b32 v255, s0, 12
	s_lshl_b32 s64, s64, 5
	s_mov_b32 s5, 0
	v_writelane_b32 v255, s1, 13
	s_lshl_b32 s0, s6, 6
	s_add_u32 s0, s62, s0
	s_addc_u32 s1, s63, 0
	s_add_u32 s94, s0, 0x16800000
	s_addc_u32 s95, s1, 0
	s_lshl_b32 s1, s6, 2
	s_lshl_b32 s0, s6, 1
	s_add_i32 s3, s1, 0
	s_lshr_b32 s1, s33, 7
	s_and_b32 s0, s0, 2
	s_add_i32 s3, s3, 0x21800
	s_lshl_b32 s34, s1, 5
	s_cmp_le_u32 s0, s1
	s_cselect_b64 s[96:97], -1, 0
	s_lshl_b32 s35, s0, 5
	s_or_b32 s4, s0, 1
	s_cmp_lt_u32 s0, s1
	s_cselect_b64 s[50:51], -1, 0
	s_lshl_b32 s82, s0, 6
	s_lshl_b32 s73, s4, 5
	s_lshl_b32 s84, s4, 6
	s_cmpk_lt_u32 s33, 0x1000
	s_cselect_b64 s[0:1], -1, 0
	v_writelane_b32 v255, s0, 14
	s_mov_b32 s33, 0xf800000
	s_movk_i32 s4, 0x90
	v_writelane_b32 v255, s1, 15
	s_lshl_b64 s[0:1], s[78:79], 2
	v_writelane_b32 v255, s0, 16
	v_writelane_b32 v253, s76, 5
	s_mov_b64 s[8:9], 0x30000
	v_writelane_b32 v255, s1, 17
	s_add_u32 s0, s60, 0x1000
	s_addc_u32 s1, s61, 0
	v_writelane_b32 v255, s0, 18
	v_writelane_b32 v253, s77, 6
	s_add_i32 s31, 0, 0x23fc0
	v_writelane_b32 v255, s1, 19
	s_mov_b32 s0, 1
	v_writelane_b32 v255, s0, 20
	s_lshl_b32 s0, s6, 8
	v_writelane_b32 v255, s0, 21
	s_mov_b32 s0, s6
	v_writelane_b32 v255, s0, 22
	v_writelane_b32 v253, s78, 7
	v_writelane_b32 v253, s79, 8
	v_writelane_b32 v255, s1, 23
	s_lshl_b32 s0, s6, 10
	v_writelane_b32 v255, s0, 24
	s_add_i32 s0, 0, 0x23fe0
	v_writelane_b32 v255, s0, 25
	s_add_i32 s0, 0, 0x23fe4
	v_writelane_b32 v255, s0, 26
	s_mov_b64 s[6:7], 0x10000
	v_cmp_eq_u32_e64 s[0:1], 0, v0
	s_mov_b32 s65, s31
	s_nop 0
	v_writelane_b32 v255, s0, 27
	s_nop 1
	v_writelane_b32 v255, s1, 28
	v_writelane_b32 v255, s82, 29
	v_writelane_b32 v255, s84, 30
	v_writelane_b32 v255, s2, 31
	s_mov_b64 s[0:1], -1
	v_writelane_b32 v255, s93, 32
	s_branch .LBB0_132

; __device__ __forceinline__ void xcd_barrier(const XcdBarrier& b) {
;     asm volatile("s_waitcnt vmcnt(0)" ::: "memory");
;     __syncthreads();
;     if (threadIdx.x == 0) {
;         unsigned* bar = b.bar;
;         __builtin_amdgcn_s_waitcnt(0);
;         unsigned nloc = b.st[0], nx = b.st[1];
;         if (nloc == 0u) { xcd_barrier_complete(bar, b.x, nloc, nx); b.st[0] = nloc; b.st[1] = nx; }
; __global__ void __launch_bounds__(NTHR, 2) fwd_kernel(Args args) {
;     ...
;     int bx = blockIdx.x;
.LBB0_872:
	v_readlane_b32 s5, v255, 45
	s_add_i32 s5, s5, 5
	s_cmp_lt_i32 s5, s77
	s_cselect_b64 s[14:15], -1, 0
	s_and_b64 s[0:1], s[0:1], s[14:15]
	v_readlane_b32 s14, v255, 49
	v_readlane_b32 s15, v255, 50
	s_nop 1
	s_and_b64 s[0:1], s[0:1], s[14:15]
	v_writelane_b32 v255, s5, 45
	s_andn2_b64 vcc, exec, s[0:1]
	s_cbranch_vccnz .LBB0_136
	v_readlane_b32 s14, v253, 23
	v_readlane_b32 s15, v253, 24
	s_mov_b64 s[0:1], -1
	s_and_b64 vcc, exec, s[14:15]
	s_cbranch_vccz .LBB0_927
	s_waitcnt vmcnt(0)
	s_waitcnt lgkmcnt(0)
	s_barrier
	s_mov_b64 s[0:1], exec
	v_readlane_b32 s14, v253, 2
	v_readlane_b32 s15, v253, 3
	s_and_b64 s[14:15], s[0:1], s[14:15]
	s_mov_b64 exec, s[14:15]
	s_cbranch_execz .LBB0_926
	v_readlane_b32 s5, v255, 25
	s_waitcnt vmcnt(0) expcnt(0) lgkmcnt(0)
	s_nop 0
	v_mov_b32_e32 v0, s5
	ds_read_b32 v3, v0
	v_readlane_b32 s5, v255, 26
	s_waitcnt lgkmcnt(0)
	v_cmp_ne_u32_e32 vcc, 0, v3
	v_mov_b32_e32 v0, s5
	ds_read_b32 v2, v0
	s_cbranch_vccnz .LBB0_890
	s_mov_b32 s5, 1
	s_branch .LBB0_878
